# accumulator zeroing at GEMM unit heads with 64-bit moves (64 instead of 128 instructions)
# speedup vs baseline: 1.0284x; 1.0061x over previous
.LBB0_231:
	s_ashr_i32 s77, s76, 31
	s_lshl_b64 s[66:67], s[76:77], 19
	s_add_u32 s80, s12, s66
	s_addc_u32 s81, s13, s67
	s_and_b64 s[66:67], s[78:79], exec
	s_cselect_b32 s66, s81, s85
	s_cselect_b32 s67, s80, s84
	s_ashr_i32 s75, s74, 31
	s_lshl_b64 s[68:69], s[74:75], 19
	s_add_u32 s82, s5, s68
	s_addc_u32 s83, s20, s69
	s_and_b64 s[68:69], s[78:79], exec
	s_cselect_b32 s68, s83, s87
	s_cselect_b32 s69, s82, s86
	s_add_u32 s84, s84, 0x40080
	s_addc_u32 s85, s85, 0
	s_add_u32 s75, s86, 0x100
	v_mov_b64_e32 v[0:1], 0
	s_addc_u32 s77, s87, 0
	s_mov_b32 s90, -2
	v_mov_b64_e32 v[2:3], 0
	v_mov_b64_e32 v[4:5], 0
	v_mov_b64_e32 v[6:7], 0
	v_mov_b64_e32 v[8:9], 0
	v_mov_b64_e32 v[10:11], 0
	v_mov_b64_e32 v[12:13], 0
	v_mov_b64_e32 v[14:15], 0
	v_mov_b64_e32 v[16:17], 0
	v_mov_b64_e32 v[18:19], 0
	v_mov_b64_e32 v[20:21], 0
	v_mov_b64_e32 v[22:23], 0
	v_mov_b64_e32 v[24:25], 0
	v_mov_b64_e32 v[26:27], 0
	v_mov_b64_e32 v[28:29], 0
	v_mov_b64_e32 v[30:31], 0
	v_mov_b64_e32 v[32:33], 0
	v_mov_b64_e32 v[34:35], 0
	v_mov_b64_e32 v[36:37], 0
	v_mov_b64_e32 v[38:39], 0
	v_mov_b64_e32 v[40:41], 0
	v_mov_b64_e32 v[42:43], 0
	v_mov_b64_e32 v[44:45], 0
	v_mov_b64_e32 v[46:47], 0
	v_mov_b64_e32 v[48:49], 0
	v_mov_b64_e32 v[50:51], 0
	v_mov_b64_e32 v[52:53], 0
	v_mov_b64_e32 v[54:55], 0
	v_mov_b64_e32 v[56:57], 0
	v_mov_b64_e32 v[58:59], 0
	v_mov_b64_e32 v[60:61], 0
	v_mov_b64_e32 v[62:63], 0
	v_mov_b64_e32 v[64:65], 0
	v_mov_b64_e32 v[66:67], 0
	v_mov_b64_e32 v[68:69], 0
	v_mov_b64_e32 v[70:71], 0
	v_mov_b64_e32 v[72:73], 0
	v_mov_b64_e32 v[74:75], 0
	v_mov_b64_e32 v[76:77], 0
	v_mov_b64_e32 v[78:79], 0
	v_mov_b64_e32 v[80:81], 0
	v_mov_b64_e32 v[82:83], 0
	v_mov_b64_e32 v[84:85], 0
	v_mov_b64_e32 v[86:87], 0
	v_mov_b64_e32 v[88:89], 0
	v_mov_b64_e32 v[90:91], 0
	v_mov_b64_e32 v[92:93], 0
	v_mov_b64_e32 v[94:95], 0
	v_mov_b64_e32 v[100:101], 0
	v_mov_b64_e32 v[102:103], 0
	v_mov_b64_e32 v[104:105], 0
	v_mov_b64_e32 v[106:107], 0
	v_mov_b64_e32 v[108:109], 0
	v_mov_b64_e32 v[110:111], 0
	v_mov_b64_e32 v[112:113], 0
	v_mov_b64_e32 v[114:115], 0
	v_mov_b64_e32 v[116:117], 0
	v_mov_b64_e32 v[118:119], 0
	v_mov_b64_e32 v[120:121], 0
	v_mov_b64_e32 v[122:123], 0
	v_mov_b64_e32 v[124:125], 0
	v_mov_b64_e32 v[126:127], 0
	v_mov_b64_e32 v[128:129], 0
	v_mov_b64_e32 v[130:131], 0
	s_waitcnt vmcnt(0)

.LBB0_309:
	s_add_u32 s84, s84, 0x80
	s_addc_u32 s85, s85, 0
	s_add_u32 s26, s86, 0x100
	v_mov_b64_e32 v[0:1], 0
	s_addc_u32 s27, s87, 0
	s_mov_b32 s0, 0
	s_waitcnt lgkmcnt(0)
	v_mov_b64_e32 v[2:3], 0
	v_mov_b64_e32 v[4:5], 0
	v_mov_b64_e32 v[6:7], 0
	v_mov_b64_e32 v[8:9], 0
	v_mov_b64_e32 v[10:11], 0
	v_mov_b64_e32 v[12:13], 0
	v_mov_b64_e32 v[14:15], 0
	v_mov_b64_e32 v[16:17], 0
	v_mov_b64_e32 v[18:19], 0
	v_mov_b64_e32 v[20:21], 0
	v_mov_b64_e32 v[22:23], 0
	v_mov_b64_e32 v[24:25], 0
	v_mov_b64_e32 v[26:27], 0
	v_mov_b64_e32 v[28:29], 0
	v_mov_b64_e32 v[30:31], 0
	v_mov_b64_e32 v[32:33], 0
	v_mov_b64_e32 v[34:35], 0
	v_mov_b64_e32 v[36:37], 0
	v_mov_b64_e32 v[38:39], 0
	v_mov_b64_e32 v[40:41], 0
	v_mov_b64_e32 v[42:43], 0
	v_mov_b64_e32 v[44:45], 0
	v_mov_b64_e32 v[46:47], 0
	v_mov_b64_e32 v[48:49], 0
	v_mov_b64_e32 v[50:51], 0
	v_mov_b64_e32 v[52:53], 0
	v_mov_b64_e32 v[54:55], 0
	v_mov_b64_e32 v[56:57], 0
	v_mov_b64_e32 v[58:59], 0
	v_mov_b64_e32 v[60:61], 0
	v_mov_b64_e32 v[62:63], 0
	v_mov_b64_e32 v[64:65], 0
	v_mov_b64_e32 v[66:67], 0
	v_mov_b64_e32 v[68:69], 0
	v_mov_b64_e32 v[70:71], 0
	v_mov_b64_e32 v[72:73], 0
	v_mov_b64_e32 v[74:75], 0
	v_mov_b64_e32 v[76:77], 0
	v_mov_b64_e32 v[78:79], 0
	v_mov_b64_e32 v[80:81], 0
	v_mov_b64_e32 v[82:83], 0
	v_mov_b64_e32 v[84:85], 0
	v_mov_b64_e32 v[86:87], 0
	v_mov_b64_e32 v[88:89], 0
	v_mov_b64_e32 v[90:91], 0
	v_mov_b64_e32 v[92:93], 0
	v_mov_b64_e32 v[94:95], 0
	v_mov_b64_e32 v[100:101], 0
	v_mov_b64_e32 v[102:103], 0
	v_mov_b64_e32 v[104:105], 0
	v_mov_b64_e32 v[106:107], 0
	v_mov_b64_e32 v[108:109], 0
	v_mov_b64_e32 v[110:111], 0
	v_mov_b64_e32 v[112:113], 0
	v_mov_b64_e32 v[114:115], 0
	v_mov_b64_e32 v[116:117], 0
	v_mov_b64_e32 v[118:119], 0
	v_mov_b64_e32 v[120:121], 0
	v_mov_b64_e32 v[122:123], 0
	v_mov_b64_e32 v[124:125], 0
	v_mov_b64_e32 v[126:127], 0
	v_mov_b64_e32 v[128:129], 0
	v_mov_b64_e32 v[130:131], 0
	s_waitcnt vmcnt(0)

.LBB0_345:
	s_ashr_i32 s71, s70, 31
	s_lshl_b64 s[56:57], s[70:71], 19
	s_add_u32 s74, s12, s56
	s_addc_u32 s75, s13, s57
	s_and_b64 s[56:57], s[72:73], exec
	s_cselect_b32 s27, s75, s79
	s_cselect_b32 s42, s74, s78
	s_ashr_i32 s69, s68, 31
	s_lshl_b64 s[56:57], s[68:69], 19
	s_add_u32 s76, s4, s56
	s_addc_u32 s77, s5, s57
	s_and_b64 s[56:57], s[72:73], exec
	s_cselect_b32 s56, s77, s81
	s_cselect_b32 s57, s76, s80
	s_add_u32 s78, s78, 0x40080
	s_addc_u32 s79, s79, 0
	s_add_u32 s69, s80, 0x100
	v_mov_b64_e32 v[0:1], 0
	s_addc_u32 s71, s81, 0
	s_mov_b32 s84, -2
	v_mov_b64_e32 v[2:3], 0
	v_mov_b64_e32 v[4:5], 0
	v_mov_b64_e32 v[6:7], 0
	v_mov_b64_e32 v[8:9], 0
	v_mov_b64_e32 v[10:11], 0
	v_mov_b64_e32 v[12:13], 0
	v_mov_b64_e32 v[14:15], 0
	v_mov_b64_e32 v[16:17], 0
	v_mov_b64_e32 v[18:19], 0
	v_mov_b64_e32 v[20:21], 0
	v_mov_b64_e32 v[22:23], 0
	v_mov_b64_e32 v[24:25], 0
	v_mov_b64_e32 v[26:27], 0
	v_mov_b64_e32 v[28:29], 0
	v_mov_b64_e32 v[30:31], 0
	v_mov_b64_e32 v[32:33], 0
	v_mov_b64_e32 v[34:35], 0
	v_mov_b64_e32 v[36:37], 0
	v_mov_b64_e32 v[38:39], 0
	v_mov_b64_e32 v[40:41], 0
	v_mov_b64_e32 v[42:43], 0
	v_mov_b64_e32 v[44:45], 0
	v_mov_b64_e32 v[46:47], 0
	v_mov_b64_e32 v[48:49], 0
	v_mov_b64_e32 v[50:51], 0
	v_mov_b64_e32 v[52:53], 0
	v_mov_b64_e32 v[54:55], 0
	v_mov_b64_e32 v[56:57], 0
	v_mov_b64_e32 v[58:59], 0
	v_mov_b64_e32 v[60:61], 0
	v_mov_b64_e32 v[62:63], 0
	v_mov_b64_e32 v[64:65], 0
	v_mov_b64_e32 v[66:67], 0
	v_mov_b64_e32 v[68:69], 0
	v_mov_b64_e32 v[70:71], 0
	v_mov_b64_e32 v[72:73], 0
	v_mov_b64_e32 v[74:75], 0
	v_mov_b64_e32 v[76:77], 0
	v_mov_b64_e32 v[78:79], 0
	v_mov_b64_e32 v[80:81], 0
	v_mov_b64_e32 v[82:83], 0
	v_mov_b64_e32 v[84:85], 0
	v_mov_b64_e32 v[86:87], 0
	v_mov_b64_e32 v[88:89], 0
	v_mov_b64_e32 v[90:91], 0
	v_mov_b64_e32 v[92:93], 0
	v_mov_b64_e32 v[94:95], 0
	v_mov_b64_e32 v[100:101], 0
	v_mov_b64_e32 v[102:103], 0
	v_mov_b64_e32 v[104:105], 0
	v_mov_b64_e32 v[106:107], 0
	v_mov_b64_e32 v[108:109], 0
	v_mov_b64_e32 v[110:111], 0
	v_mov_b64_e32 v[112:113], 0
	v_mov_b64_e32 v[114:115], 0
	v_mov_b64_e32 v[116:117], 0
	v_mov_b64_e32 v[118:119], 0
	v_mov_b64_e32 v[120:121], 0
	v_mov_b64_e32 v[122:123], 0
	v_mov_b64_e32 v[124:125], 0
	v_mov_b64_e32 v[126:127], 0
	v_mov_b64_e32 v[128:129], 0
	v_mov_b64_e32 v[130:131], 0
	s_waitcnt vmcnt(0)
